# final norm: final_g chunks loaded once before the row loop (were re-loaded behind every store with a vmcnt(0) that waited for the store ack)
# speedup vs baseline: 1.0024x; 1.0021x over previous
; __device__ __forceinline__ float bf_lo(unsigned u) { return __uint_as_float(u << 16); }
; __device__ __forceinline__ float bf_hi(unsigned u) { return __uint_as_float(u & 0xffff0000u); }
; __device__ __forceinline__ void final_norm_phase(Frame& F) {
;     ...
;     const f32x4* gp = (const f32x4*)F.in[I_FING] + lane;
;     for (int r = gw; r < MLAT; r += NGW) {
;         f32x4* xr = (f32x4*)(F.out + (size_t)r * D) + lane; const u32x2* xb = (const u32x2*)((const bf16_t*)(F.ws + WS_XB) + (size_t)r * D) + lane;
;         const u32x2* yp = (const u32x2*)((const bf16_t*)(F.ws + WS_Y) + (size_t)r * D) + lane; const u32x2* yp2 = (const u32x2*)((const bf16_t*)(F.ws + WS_Y2) + (size_t)r * D) + lane;
;         const f32x4* gq = (const f32x4*)((const float*)(F.ws + WS_MOD) + ((size_t)(DEPTH - 1) * 9 + (r >> 11)) * MODW + 2 * D) + lane; const f32x4* gq2 = gq + 3 * D / 4;
;         f32x4 v[8]; float ss = 0.f;
; #pragma unroll
;         for (int j = 0; j < 8; ++j) { const u32x2 yy = __builtin_nontemporal_load(yp + 64 * j), y2 = __builtin_nontemporal_load(yp2 + 64 * j);
;             const f32x4 y4 = {bf_lo(yy.x), bf_hi(yy.x), bf_lo(yy.y), bf_hi(yy.y)}, z4 = {bf_lo(y2.x), bf_hi(y2.x), bf_lo(y2.y), bf_hi(y2.y)};
;             const u32x2 xw = __builtin_nontemporal_load(xb + 64 * j); v[j] = (f32x4){bf_lo(xw.x), bf_hi(xw.x), bf_lo(xw.y), bf_hi(xw.y)} + gq[64 * j] * y4; v[j] += gq2[64 * j] * z4;
.LBB0_1399:
	v_readlane_b32 s2, v251, 2
	v_readlane_b32 s3, v251, 3
	s_cmp_gt_i32 s2, 42
	s_cselect_b64 s[0:1], -1, 0
	s_cmp_lt_i32 s3, 43
	s_cselect_b64 s[2:3], -1, 0
	s_or_b64 s[0:1], s[0:1], s[2:3]
	s_and_b64 vcc, exec, s[0:1]
	v_readlane_b32 s12, v251, 21
	s_cbranch_vccnz .LBB0_1455
	v_readlane_b32 s0, v253, 35
	v_readlane_b32 s1, v253, 36
	v_readlane_b32 s14, v255, 4
	v_readlane_b32 s16, v255, 10
	s_and_b64 vcc, exec, s[0:1]
	v_readlane_b32 s15, v255, 5
	v_readlane_b32 s17, v255, 11
	s_waitcnt vmcnt(0)
	v_mbcnt_lo_u32_b32 v4, -1, 0
	v_mbcnt_hi_u32_b32 v4, -1, v4
	s_cbranch_vccz .LBB0_1403
	v_ashrrev_i32_e32 v5, 31, v4
	v_lshlrev_b64 v[0:1], 4, v[4:5]
	v_lshl_add_u64 v[6:7], s[62:63], 0, v[0:1]
	s_mov_b64 s[0:1], 0x1400
	v_lshl_add_u64 v[10:11], v[6:7], 0, s[0:1]
	s_mov_b64 s[0:1], 0x1800
	v_lshl_add_u64 v[12:13], v[6:7], 0, s[0:1]
	s_mov_b64 s[0:1], 0x1c00
	v_lshl_add_u64 v[14:15], v[6:7], 0, s[0:1]
	s_lshl_b64 s[0:1], s[14:15], 12
	s_add_u32 s0, s66, s0
	s_addc_u32 s1, s67, s1
	v_lshl_add_u64 v[2:3], v[4:5], 3, s[0:1]
	s_mov_b64 s[0:1], 0x38600000
	v_lshl_add_u64 v[16:17], v[2:3], 0, s[0:1]
	s_lshl_b64 s[0:1], s[72:73], 12
	v_readlane_b32 s4, v255, 6
	v_readlane_b32 s5, v255, 7
	s_add_u32 s4, s64, s4
	s_addc_u32 s5, s65, s5
	s_mov_b64 s[2:3], 0x1000
	v_lshl_add_u64 v[0:1], s[4:5], 0, v[0:1]
	v_lshl_add_u64 v[8:9], v[6:7], 0, s[2:3]
	v_lshl_add_u64 v[18:19], v[0:1], 0, s[2:3]
	s_mov_b64 s[2:3], 0x104000
	s_mov_b32 s4, 0x16d00000
	s_mov_b32 s5, 0x10a000
	s_mov_b32 s6, 0x105000
	s_mov_b32 s7, 0x10b000
	v_mov_b32_e32 v32, 0x358637bd
	v_mov_b32_e32 v33, 0x3a000000
	s_mov_b32 s8, 0x800000
	global_load_dwordx4 v[184:187], v[6:7], off offset:1024
	global_load_dwordx4 v[188:191], v[6:7], off offset:2048
	global_load_dwordx4 v[192:195], v[6:7], off offset:3072
	global_load_dwordx4 v[196:199], v[8:9], off
	global_load_dwordx4 v[200:203], v[10:11], off
	global_load_dwordx4 v[204:207], v[12:13], off
	global_load_dwordx4 v[208:211], v[14:15], off
	s_waitcnt vmcnt(0)
.LBB0_1402:
	s_ashr_i32 s9, s14, 11
	s_add_i32 s9, s9, 27
	v_add_co_u32_e32 v28, vcc, 0xdd00000, v16
	s_mul_hi_i32 s11, s9, 0xc000
	s_mul_i32 s9, s9, 0xc000
	v_addc_co_u32_e32 v29, vcc, 0, v17, vcc
	s_add_u32 s10, s66, s9
	v_add_co_u32_e32 v34, vcc, s4, v16
	s_addc_u32 s11, s67, s11
	s_nop 0
	v_addc_co_u32_e32 v35, vcc, 0, v17, vcc
	v_lshl_add_u64 v[66:67], v[4:5], 4, s[10:11]
	v_lshl_add_u64 v[42:43], v[66:67], 0, s[2:3]
	v_add_co_u32_e32 v62, vcc, s6, v66
	global_load_dwordx2 v[20:21], v[16:17], off nt
	global_load_dwordx2 v[22:23], v[16:17], off offset:512 nt
	global_load_dwordx2 v[24:25], v[16:17], off offset:1024 nt
	global_load_dwordx2 v[26:27], v[16:17], off offset:1536 nt
	global_load_dwordx2 v[30:31], v[16:17], off offset:2048 nt
	global_load_dwordx2 v[98:99], v[16:17], off offset:2560 nt
	global_load_dwordx2 v[100:101], v[16:17], off offset:3072 nt
	global_load_dwordx2 v[102:103], v[16:17], off offset:3584 nt
	global_load_dwordx4 v[0:3], v[6:7], off
	global_load_dwordx2 v[104:105], v[28:29], off nt
	global_load_dwordx2 v[106:107], v[28:29], off offset:512 nt
	global_load_dwordx2 v[108:109], v[28:29], off offset:1024 nt
	global_load_dwordx2 v[110:111], v[28:29], off offset:1536 nt
	global_load_dwordx2 v[112:113], v[28:29], off offset:2048 nt
	global_load_dwordx2 v[114:115], v[28:29], off offset:2560 nt
	global_load_dwordx2 v[116:117], v[28:29], off offset:3072 nt
	s_nop 0
	global_load_dwordx2 v[28:29], v[28:29], off offset:3584 nt
	s_nop 0
	global_load_dwordx2 v[118:119], v[34:35], off nt
	global_load_dwordx2 v[120:121], v[34:35], off offset:512 nt
	global_load_dwordx2 v[122:123], v[34:35], off offset:1024 nt
	global_load_dwordx2 v[124:125], v[34:35], off offset:1536 nt
	global_load_dwordx2 v[126:127], v[34:35], off offset:2048 nt
	global_load_dwordx2 v[128:129], v[34:35], off offset:2560 nt
	global_load_dwordx2 v[130:131], v[34:35], off offset:3072 nt
	global_load_dwordx2 v[132:133], v[34:35], off offset:3584 nt
	v_addc_co_u32_e32 v63, vcc, 0, v67, vcc
	global_load_dwordx4 v[34:37], v[42:43], off offset:1024
	global_load_dwordx4 v[38:41], v[42:43], off offset:2048
	s_nop 0
	global_load_dwordx4 v[42:45], v[42:43], off offset:3072
	s_nop 0
	global_load_dwordx4 v[46:49], v[62:63], off offset:-4096
	v_add_co_u32_e32 v74, vcc, s5, v66
	global_load_dwordx4 v[50:53], v[62:63], off
	global_load_dwordx4 v[54:57], v[62:63], off offset:1024
	global_load_dwordx4 v[58:61], v[62:63], off offset:2048
	s_nop 0
	global_load_dwordx4 v[62:65], v[62:63], off offset:3072
	v_addc_co_u32_e32 v75, vcc, 0, v67, vcc
	v_add_co_u32_e32 v94, vcc, s7, v66
	v_mov_b32_e32 v182, 0
	s_nop 0
	v_addc_co_u32_e32 v95, vcc, 0, v67, vcc
	global_load_dwordx4 v[66:69], v[74:75], off offset:1024
	global_load_dwordx4 v[70:73], v[74:75], off offset:2048
	s_nop 0
	global_load_dwordx4 v[74:77], v[74:75], off offset:3072
	s_nop 0
	global_load_dwordx4 v[78:81], v[94:95], off offset:-4096
	global_load_dwordx4 v[82:85], v[94:95], off
	global_load_dwordx4 v[86:89], v[94:95], off offset:1024
	global_load_dwordx4 v[90:93], v[94:95], off offset:2048
	s_nop 0
	global_load_dwordx4 v[94:97], v[94:95], off offset:3072
	v_mov_b32_e32 v183, 0
	s_add_i32 s14, s14, s72
	v_lshl_add_u64 v[16:17], v[16:17], 0, s[0:1]
	s_cmpk_lt_i32 s14, 0x4000
	s_waitcnt vmcnt(31)
	v_lshlrev_b32_e32 v150, 16, v104
	v_and_b32_e32 v151, 0xffff0000, v104
	v_lshlrev_b32_e32 v104, 16, v105
	v_and_b32_e32 v105, 0xffff0000, v105
	s_waitcnt vmcnt(30)
	v_lshlrev_b32_e32 v152, 16, v106
	v_and_b32_e32 v153, 0xffff0000, v106
	v_lshlrev_b32_e32 v106, 16, v107
	v_and_b32_e32 v107, 0xffff0000, v107
	s_waitcnt vmcnt(29)
; __device__ __forceinline__ float bf_lo(unsigned u) { return __uint_as_float(u << 16); }
; __device__ __forceinline__ float bf_hi(unsigned u) { return __uint_as_float(u & 0xffff0000u); }
; __device__ __forceinline__ void final_norm_phase(Frame& F) {
;     ...
;         for (int j = 0; j < 8; ++j) { const u32x2 yy = __builtin_nontemporal_load(yp + 64 * j), y2 = __builtin_nontemporal_load(yp2 + 64 * j);
;             const f32x4 y4 = {bf_lo(yy.x), bf_hi(yy.x), bf_lo(yy.y), bf_hi(yy.y)}, z4 = {bf_lo(y2.x), bf_hi(y2.x), bf_lo(y2.y), bf_hi(y2.y)};
;             const u32x2 xw = __builtin_nontemporal_load(xb + 64 * j); v[j] = (f32x4){bf_lo(xw.x), bf_hi(xw.x), bf_lo(xw.y), bf_hi(xw.y)} + gq[64 * j] * y4; v[j] += gq2[64 * j] * z4;
;             ss += (v[j].x * v[j].x + v[j].y * v[j].y) + (v[j].z * v[j].z + v[j].w * v[j].w); }
	v_lshlrev_b32_e32 v154, 16, v108
	v_and_b32_e32 v155, 0xffff0000, v108
	v_lshlrev_b32_e32 v108, 16, v109
	v_and_b32_e32 v109, 0xffff0000, v109
	s_waitcnt vmcnt(23)
	v_lshlrev_b32_e32 v166, 16, v118
	v_and_b32_e32 v167, 0xffff0000, v118
	v_lshlrev_b32_e32 v118, 16, v119
	v_and_b32_e32 v119, 0xffff0000, v119
	s_waitcnt vmcnt(22)
	v_lshlrev_b32_e32 v168, 16, v120
	v_and_b32_e32 v169, 0xffff0000, v120
	v_lshlrev_b32_e32 v120, 16, v121
	v_and_b32_e32 v121, 0xffff0000, v121
	s_waitcnt vmcnt(21)
	v_lshlrev_b32_e32 v170, 16, v122
	v_and_b32_e32 v171, 0xffff0000, v122
	v_lshlrev_b32_e32 v122, 16, v123
	v_and_b32_e32 v123, 0xffff0000, v123
	v_lshlrev_b32_e32 v134, 16, v20
	v_and_b32_e32 v135, 0xffff0000, v20
	v_lshlrev_b32_e32 v20, 16, v21
	v_and_b32_e32 v21, 0xffff0000, v21
	v_lshlrev_b32_e32 v136, 16, v22
	v_and_b32_e32 v137, 0xffff0000, v22
	v_lshlrev_b32_e32 v22, 16, v23
	v_and_b32_e32 v23, 0xffff0000, v23
	v_lshlrev_b32_e32 v138, 16, v24
	v_and_b32_e32 v139, 0xffff0000, v24
	v_lshlrev_b32_e32 v24, 16, v25
	v_and_b32_e32 v25, 0xffff0000, v25
	v_lshlrev_b32_e32 v156, 16, v110
	v_and_b32_e32 v157, 0xffff0000, v110
	v_lshlrev_b32_e32 v110, 16, v111
	v_and_b32_e32 v111, 0xffff0000, v111
	s_waitcnt vmcnt(20)
	v_lshlrev_b32_e32 v172, 16, v124
	v_and_b32_e32 v173, 0xffff0000, v124
	v_lshlrev_b32_e32 v124, 16, v125
	v_and_b32_e32 v125, 0xffff0000, v125
	s_waitcnt vmcnt(15)
	v_pk_fma_f32 v[36:37], v[36:37], v[106:107], v[120:121]
	v_pk_fma_f32 v[34:35], v[34:35], v[152:153], v[168:169]
	s_waitcnt vmcnt(14)
	v_pk_fma_f32 v[40:41], v[40:41], v[108:109], v[122:123]
	s_waitcnt vmcnt(12)
	v_pk_fma_f32 v[46:47], v[46:47], v[150:151], v[166:167]
	v_pk_fma_f32 v[48:49], v[48:49], v[104:105], v[118:119]
	v_lshlrev_b32_e32 v140, 16, v26
	v_and_b32_e32 v141, 0xffff0000, v26
	v_lshlrev_b32_e32 v26, 16, v27
	v_and_b32_e32 v27, 0xffff0000, v27
	v_pk_fma_f32 v[38:39], v[38:39], v[154:155], v[170:171]
	v_pk_fma_f32 v[44:45], v[44:45], v[110:111], v[124:125]
	s_waitcnt vmcnt(7)
	v_pk_fma_f32 v[22:23], v[68:69], v[22:23], v[36:37]
	v_pk_fma_f32 v[34:35], v[66:67], v[136:137], v[34:35]
	s_waitcnt vmcnt(6)
	v_pk_fma_f32 v[24:25], v[72:73], v[24:25], v[40:41]
	s_waitcnt vmcnt(4)
	v_pk_fma_f32 v[20:21], v[80:81], v[20:21], v[48:49]
	v_pk_fma_f32 v[40:41], v[78:79], v[134:135], v[46:47]
	v_lshlrev_b32_e32 v164, 16, v28
	v_and_b32_e32 v165, 0xffff0000, v28
	v_lshlrev_b32_e32 v28, 16, v29
	v_and_b32_e32 v29, 0xffff0000, v29
	v_lshlrev_b32_e32 v180, 16, v132
	v_and_b32_e32 v181, 0xffff0000, v132
	v_lshlrev_b32_e32 v132, 16, v133
	v_and_b32_e32 v133, 0xffff0000, v133
	v_pk_fma_f32 v[42:43], v[42:43], v[156:157], v[172:173]
	v_pk_fma_f32 v[36:37], v[70:71], v[138:139], v[38:39]
	v_pk_fma_f32 v[26:27], v[76:77], v[26:27], v[44:45]
	v_mov_b32_e32 v45, v35
	v_mov_b32_e32 v49, v23
	v_mov_b32_e32 v44, v41
	v_mov_b32_e32 v48, v21
	v_lshlrev_b32_e32 v158, 16, v112
	v_and_b32_e32 v159, 0xffff0000, v112
	v_lshlrev_b32_e32 v112, 16, v113
	v_and_b32_e32 v113, 0xffff0000, v113
	v_lshlrev_b32_e32 v174, 16, v126
	v_and_b32_e32 v175, 0xffff0000, v126
	v_lshlrev_b32_e32 v126, 16, v127
	v_and_b32_e32 v127, 0xffff0000, v127
	v_pk_fma_f32 v[28:29], v[64:65], v[28:29], v[132:133]
	v_pk_fma_f32 v[38:39], v[74:75], v[140:141], v[42:43]
	v_mov_b32_e32 v43, v34
	v_mov_b32_e32 v47, v22
	v_pk_mul_f32 v[64:65], v[24:25], v[24:25]
	v_pk_mul_f32 v[66:67], v[36:37], v[36:37]
	v_mov_b32_e32 v42, v40
	v_mov_b32_e32 v46, v20
	v_pk_mul_f32 v[44:45], v[44:45], v[44:45]
	v_pk_mul_f32 v[48:49], v[48:49], v[48:49]
	v_lshlrev_b32_e32 v142, 16, v30
	v_and_b32_e32 v143, 0xffff0000, v30
	v_lshlrev_b32_e32 v30, 16, v31
	v_and_b32_e32 v31, 0xffff0000, v31
	v_lshlrev_b32_e32 v160, 16, v114
	v_and_b32_e32 v161, 0xffff0000, v114
	v_lshlrev_b32_e32 v114, 16, v115
	v_and_b32_e32 v115, 0xffff0000, v115
	v_lshlrev_b32_e32 v176, 16, v128
	v_and_b32_e32 v177, 0xffff0000, v128
	v_lshlrev_b32_e32 v128, 16, v129
	v_and_b32_e32 v129, 0xffff0000, v129
	v_pk_fma_f32 v[50:51], v[50:51], v[158:159], v[174:175]
	v_pk_fma_f32 v[52:53], v[52:53], v[112:113], v[126:127]
	v_pk_mov_b32 v[70:71], v[66:67], v[64:65] op_sel:[1,0]
	v_mov_b32_e32 v67, v65
	v_pk_fma_f32 v[42:43], v[42:43], v[42:43], v[44:45]
	v_pk_fma_f32 v[44:45], v[46:47], v[46:47], v[48:49]
	v_lshlrev_b32_e32 v144, 16, v98
	v_and_b32_e32 v145, 0xffff0000, v98
	v_lshlrev_b32_e32 v98, 16, v99
	v_and_b32_e32 v99, 0xffff0000, v99
	v_pk_fma_f32 v[54:55], v[54:55], v[160:161], v[176:177]
	v_pk_fma_f32 v[56:57], v[56:57], v[114:115], v[128:129]
	s_waitcnt vmcnt(3)
	v_pk_fma_f32 v[30:31], v[84:85], v[30:31], v[52:53]
	v_pk_fma_f32 v[50:51], v[82:83], v[142:143], v[50:51]
	v_mul_f32_e32 v52, v39, v39
	v_mul_f32_e32 v68, v27, v27
	v_pk_add_f32 v[66:67], v[70:71], v[66:67]
	v_pk_add_f32 v[42:43], v[42:43], v[44:45]
	v_lshlrev_b32_e32 v162, 16, v116
	v_and_b32_e32 v163, 0xffff0000, v116
	v_lshlrev_b32_e32 v116, 16, v117
	v_and_b32_e32 v117, 0xffff0000, v117
	v_lshlrev_b32_e32 v178, 16, v130
	v_and_b32_e32 v179, 0xffff0000, v130
	v_lshlrev_b32_e32 v130, 16, v131
	v_and_b32_e32 v131, 0xffff0000, v131
	s_waitcnt vmcnt(2)
; __device__ __forceinline__ float bf_lo(unsigned u) { return __uint_as_float(u << 16); }
; __device__ __forceinline__ float bf_hi(unsigned u) { return __uint_as_float(u & 0xffff0000u); }
; #define WS_SHR(c) v += __builtin_bit_cast(float, __builtin_amdgcn_update_dpp(0, __builtin_bit_cast(int, v), c, 0xf, 0xf, true))
; __device__ __forceinline__ float wave_sum(float v, int lane) {
;     (void)lane;
;     ...
;     WS_SHR(0x111); WS_SHR(0x112); WS_SHR(0x114); WS_SHR(0x118);
;     ...
;     v += __builtin_bit_cast(float, __builtin_amdgcn_update_dpp(0, __builtin_bit_cast(int, v), 0x142, 0xa, 0xf, false));
;     v += __builtin_bit_cast(float, __builtin_amdgcn_update_dpp(0, __builtin_bit_cast(int, v), 0x143, 0xc, 0xf, false));
;     return __builtin_bit_cast(float, __builtin_amdgcn_readlane(__builtin_bit_cast(int, v), 63));
; __device__ __forceinline__ void final_norm_phase(Frame& F) {
;     ...
;             const u32x2 xw = __builtin_nontemporal_load(xb + 64 * j); v[j] = (f32x4){bf_lo(xw.x), bf_hi(xw.x), bf_lo(xw.y), bf_hi(xw.y)} + gq[64 * j] * y4; v[j] += gq2[64 * j] * z4;
;             ss += (v[j].x * v[j].x + v[j].y * v[j].y) + (v[j].z * v[j].z + v[j].w * v[j].w); }
;         const float rstd = rsqrtf(wave_sum(ss, lane) * (1.0f / D) + EPS);
; #pragma unroll
;         for (int j = 0; j < 8; ++j) xr[64 * j] = v[j] * rstd * gp[64 * j];
	v_pk_fma_f32 v[56:57], v[88:89], v[98:99], v[56:57]
	v_pk_fma_f32 v[54:55], v[86:87], v[144:145], v[54:55]
	v_mul_f32_e32 v77, v50, v50
	v_mul_f32_e32 v78, v51, v51
	v_mul_f32_e32 v75, v30, v30
	v_mul_f32_e32 v79, v31, v31
	v_pk_fma_f32 v[52:53], v[38:39], v[38:39], v[52:53] op_sel_hi:[1,1,0]
	v_pk_fma_f32 v[64:65], v[26:27], v[26:27], v[68:69] op_sel_hi:[1,1,0]
	v_pk_add_f32 v[46:47], v[66:67], v[66:67] op_sel:[0,1] op_sel_hi:[1,0]
	v_pk_add_f32 v[42:43], v[42:43], v[42:43] op_sel:[0,1] op_sel_hi:[1,0]
	v_lshlrev_b32_e32 v146, 16, v100
	v_and_b32_e32 v147, 0xffff0000, v100
	v_lshlrev_b32_e32 v100, 16, v101
	v_and_b32_e32 v101, 0xffff0000, v101
	v_pk_fma_f32 v[58:59], v[58:59], v[162:163], v[178:179]
	v_pk_fma_f32 v[60:61], v[60:61], v[116:117], v[130:131]
	v_pk_mul_f32 v[68:69], v[54:55], v[54:55]
	v_pk_mul_f32 v[72:73], v[56:57], v[56:57]
	v_mov_b32_e32 v53, v75
	v_mov_b32_e32 v65, v79
	v_mov_b32_e32 v47, v78
	v_mov_b32_e32 v43, v77
	v_lshlrev_b32_e32 v148, 16, v102
	v_and_b32_e32 v149, 0xffff0000, v102
	v_lshlrev_b32_e32 v102, 16, v103
	v_and_b32_e32 v103, 0xffff0000, v103
	v_pk_fma_f32 v[62:63], v[62:63], v[164:165], v[180:181]
	s_waitcnt vmcnt(1)
	v_pk_fma_f32 v[60:61], v[92:93], v[100:101], v[60:61]
	v_pk_fma_f32 v[58:59], v[90:91], v[146:147], v[58:59]
	v_pk_mov_b32 v[70:71], v[68:69], v[72:73] op_sel:[1,0]
	v_mov_b32_e32 v69, v73
	v_pk_add_f32 v[48:49], v[52:53], v[64:65]
	v_pk_add_f32 v[42:43], v[42:43], v[46:47]
	s_waitcnt vmcnt(0)
	v_pk_fma_f32 v[28:29], v[96:97], v[102:103], v[28:29]
	v_pk_fma_f32 v[62:63], v[94:95], v[148:149], v[62:63]
	v_mul_f32_e32 v74, v59, v59
	v_mul_f32_e32 v76, v61, v61
	v_pk_add_f32 v[52:53], v[70:71], v[68:69]
	v_pk_add_f32 v[42:43], v[42:43], v[48:49]
	v_mul_f32_e32 v80, v62, v62
	v_mul_f32_e32 v81, v63, v63
	v_mul_f32_e32 v82, v28, v28
	v_mul_f32_e32 v83, v29, v29
	v_pk_fma_f32 v[72:73], v[58:59], v[58:59], v[74:75] op_sel_hi:[1,1,0]
	v_pk_fma_f32 v[74:75], v[60:61], v[60:61], v[76:77] op_sel_hi:[1,1,0]
	v_pk_add_f32 v[44:45], v[52:53], v[52:53] op_sel:[0,1] op_sel_hi:[1,0]
	v_pk_add_f32 v[42:43], v[42:43], v[42:43] op_sel:[0,1] op_sel_hi:[1,0]
	v_mov_b32_e32 v73, v82
	v_mov_b32_e32 v75, v83
	v_mov_b32_e32 v45, v81
	v_mov_b32_e32 v43, v80
	v_pk_add_f32 v[52:53], v[72:73], v[74:75]
	v_pk_add_f32 v[42:43], v[42:43], v[44:45]
	s_nop 0
	v_pk_add_f32 v[42:43], v[42:43], v[52:53]
	s_nop 0
	v_add_f32_e32 v42, v42, v43
	s_nop 1
	v_add_f32_dpp v42, v42, v42 row_shr:1 row_mask:0xf bank_mask:0xf bound_ctrl:1
	s_nop 1
	v_add_f32_dpp v42, v42, v42 row_shr:2 row_mask:0xf bank_mask:0xf bound_ctrl:1
	s_nop 1
	v_add_f32_dpp v42, v42, v42 row_shr:4 row_mask:0xf bank_mask:0xf bound_ctrl:1
	s_nop 1
	v_add_f32_dpp v42, v42, v42 row_shr:8 row_mask:0xf bank_mask:0xf bound_ctrl:1
	s_nop 1
	v_mov_b32_dpp v182, v42 row_bcast:15 row_mask:0xa bank_mask:0xf
	v_add_f32_e32 v42, v42, v182
	s_nop 1
	v_mov_b32_dpp v183, v42 row_bcast:31 row_mask:0xc bank_mask:0xf
	v_add_f32_e32 v42, v42, v183
	s_nop 0
	v_readlane_b32 s9, v42, 63
	s_nop 1
	v_fma_f32 v42, s9, v33, v32
	v_mul_f32_e32 v43, 0x4b800000, v42
	v_cmp_gt_f32_e32 vcc, s8, v42
	s_nop 1
	v_cndmask_b32_e32 v42, v42, v43, vcc
	v_rsq_f32_e32 v42, v42
	s_nop 0
	v_mul_f32_e32 v43, 0x45800000, v42
	v_cndmask_b32_e32 v42, v42, v43, vcc
	v_pk_mul_f32 v[40:41], v[40:41], v[42:43] op_sel_hi:[1,0]
	v_pk_mul_f32 v[20:21], v[20:21], v[42:43] op_sel_hi:[1,0]
	v_pk_mul_f32 v[0:1], v[0:1], v[40:41]
	v_pk_mul_f32 v[2:3], v[2:3], v[20:21]
	global_store_dwordx4 v[18:19], v[0:3], off offset:-4096
	v_pk_mul_f32 v[20:21], v[22:23], v[42:43] op_sel_hi:[1,0]
	v_pk_mul_f32 v[22:23], v[34:35], v[42:43] op_sel_hi:[1,0]
	v_pk_mul_f32 v[2:3], v[186:187], v[20:21]
	v_pk_mul_f32 v[0:1], v[184:185], v[22:23]
	global_store_dwordx4 v[18:19], v[0:3], off offset:-3072
	v_pk_mul_f32 v[20:21], v[24:25], v[42:43] op_sel_hi:[1,0]
	v_pk_mul_f32 v[22:23], v[36:37], v[42:43] op_sel_hi:[1,0]
	v_pk_mul_f32 v[2:3], v[190:191], v[20:21]
	v_pk_mul_f32 v[0:1], v[188:189], v[22:23]
	global_store_dwordx4 v[18:19], v[0:3], off offset:-2048
	v_pk_mul_f32 v[20:21], v[26:27], v[42:43] op_sel_hi:[1,0]
	v_pk_mul_f32 v[22:23], v[38:39], v[42:43] op_sel_hi:[1,0]
	v_pk_mul_f32 v[2:3], v[194:195], v[20:21]
	v_pk_mul_f32 v[0:1], v[192:193], v[22:23]
	global_store_dwordx4 v[18:19], v[0:3], off offset:-1024
	v_pk_mul_f32 v[20:21], v[30:31], v[42:43] op_sel_hi:[1,0]
	v_pk_mul_f32 v[22:23], v[50:51], v[42:43] op_sel_hi:[1,0]
	v_pk_mul_f32 v[2:3], v[198:199], v[20:21]
	v_pk_mul_f32 v[0:1], v[196:197], v[22:23]
	global_store_dwordx4 v[18:19], v[0:3], off
	v_pk_mul_f32 v[20:21], v[56:57], v[42:43] op_sel_hi:[1,0]
	v_pk_mul_f32 v[22:23], v[54:55], v[42:43] op_sel_hi:[1,0]
	v_pk_mul_f32 v[2:3], v[20:21], v[202:203]
	v_pk_mul_f32 v[0:1], v[22:23], v[200:201]
	global_store_dwordx4 v[18:19], v[0:3], off offset:1024
	v_pk_mul_f32 v[20:21], v[60:61], v[42:43] op_sel_hi:[1,0]
	v_pk_mul_f32 v[22:23], v[58:59], v[42:43] op_sel_hi:[1,0]
	v_pk_mul_f32 v[2:3], v[20:21], v[206:207]
	v_pk_mul_f32 v[0:1], v[22:23], v[204:205]
	global_store_dwordx4 v[18:19], v[0:3], off offset:2048
	v_pk_mul_f32 v[20:21], v[28:29], v[42:43] op_sel_hi:[1,0]
	v_pk_mul_f32 v[22:23], v[62:63], v[42:43] op_sel_hi:[1,0]
	v_pk_mul_f32 v[2:3], v[20:21], v[210:211]
	v_pk_mul_f32 v[0:1], v[22:23], v[208:209]
	global_store_dwordx4 v[18:19], v[0:3], off offset:3072
	v_lshl_add_u64 v[18:19], v[18:19], 0, s[16:17]
	s_cbranch_scc1 .LBB0_1402
